# attention sample rows: P.V loop batched (64 row loads in flight, rolling)
# speedup vs baseline: 1.0689x; 1.0117x over previous
; DI void attn_sample_task(LAS unsigned char* wl, int task, int l, ArgsP a, const bf16_t* Q, bf16_t* YB, int lane) {
;     ...
;     for (int t = 0; t < 4; ++t) { mx[t] = wave_max(mx[t], lane); float sum = 0.f;
;         for (int rr = 0; rr < 3; ++rr) { const int j = rr * 64 + lane; if (j < 132) { const float p = __expf(ps[t * 136 + j] - mx[t]); ps[t * 136 + j] = p; sum += p; } }
;         den[t] = wave_sum(sum, lane) + __expf(sink - mx[t]); }
;     float o[4] = {0.f, 0.f, 0.f, 0.f};
;     for (int j = 0; j < 132; ++j) { const float v = (j < 128 ? cv + (size_t)j * 128 : nv + (size_t)(j - 128) * 128)[lane];
; #pragma unroll
;         for (int t = 0; t < 4; ++t) o[t] += ps[t * 136 + j] * v; }
.LBB0_991:
	s_or_b64 exec, exec, s[2:3]
	ds_bpermute_b32 v3, v53, v2
	v_mov_b32_e32 v38, 0
	v_lshl_add_u64 v[32:33], v[22:23], 0, v[0:1]
	s_mov_b32 s22, 0
	v_mov_b32_e32 v81, v68
	s_waitcnt lgkmcnt(0)
	v_add_f32_e32 v2, v2, v3
	ds_bpermute_b32 v3, v59, v2
	v_mov_b32_e32 v39, v38
	v_mov_b32_e32 v36, v38
	v_mov_b32_e32 v37, v38
	s_waitcnt lgkmcnt(0)
	v_add_f32_e32 v3, v2, v3
	ds_bpermute_b32 v4, v64, v3
	v_or_b32_e32 v2, 0xf800, v0
	s_waitcnt lgkmcnt(0)
	v_add_f32_e32 v4, v3, v4
	ds_bpermute_b32 v5, v65, v4
	v_mov_b32_e32 v3, v1
	v_lshl_add_u64 v[34:35], v[10:11], 0, v[2:3]
	s_waitcnt lgkmcnt(0)
	v_add_f32_e32 v79, v4, v5
	ds_bpermute_b32 v80, v66, v79
	v_lshl_add_u64 v[126:127], v[32:33], 0, v[20:21]
	v_add_co_u32_e32 v126, vcc, 0x600, v126
	s_nop 1
	v_addc_co_u32_e32 v127, vcc, 0, v127, vcc
	v_lshl_add_u64 v[124:125], v[34:35], 0, v[96:97]
	v_add_u32_e32 v82, 0x100, v81
	global_load_dword v182, v[126:127], off offset:-4096
	global_load_dword v183, v[126:127], off offset:-3584
	global_load_dword v184, v[126:127], off offset:-3072
	global_load_dword v185, v[126:127], off offset:-2560
	global_load_dword v186, v[126:127], off offset:-2048
	global_load_dword v187, v[126:127], off offset:-1536
	global_load_dword v188, v[126:127], off offset:-1024
	global_load_dword v189, v[126:127], off offset:-512
	global_load_dword v190, v[126:127], off offset:0
	global_load_dword v191, v[126:127], off offset:512
	global_load_dword v192, v[126:127], off offset:1024
	global_load_dword v193, v[126:127], off offset:1536
	global_load_dword v198, v[126:127], off offset:2048
	global_load_dword v199, v[126:127], off offset:2560
	global_load_dword v200, v[126:127], off offset:3072
	global_load_dword v201, v[126:127], off offset:3584
	v_add_co_u32_e32 v126, vcc, 0x2000, v126
	s_nop 1
	v_addc_co_u32_e32 v127, vcc, 0, v127, vcc
	global_load_dword v202, v[126:127], off offset:-4096
	global_load_dword v203, v[126:127], off offset:-3584
	global_load_dword v204, v[126:127], off offset:-3072
	global_load_dword v205, v[126:127], off offset:-2560
	global_load_dword v206, v[126:127], off offset:-2048
	global_load_dword v207, v[126:127], off offset:-1536
	global_load_dword v208, v[126:127], off offset:-1024
	global_load_dword v209, v[126:127], off offset:-512
	global_load_dword v210, v[126:127], off offset:0
	global_load_dword v211, v[126:127], off offset:512
	global_load_dword v212, v[126:127], off offset:1024
	global_load_dword v213, v[126:127], off offset:1536
	global_load_dword v214, v[126:127], off offset:2048
	global_load_dword v215, v[126:127], off offset:2560
	global_load_dword v216, v[126:127], off offset:3072
	global_load_dword v217, v[126:127], off offset:3584
	v_add_co_u32_e32 v126, vcc, 0x2000, v126
	s_nop 1
	v_addc_co_u32_e32 v127, vcc, 0, v127, vcc
	global_load_dword v218, v[126:127], off offset:-4096
	global_load_dword v219, v[126:127], off offset:-3584
	global_load_dword v220, v[126:127], off offset:-3072
	global_load_dword v221, v[126:127], off offset:-2560
	global_load_dword v222, v[126:127], off offset:-2048
	global_load_dword v223, v[126:127], off offset:-1536
	global_load_dword v224, v[126:127], off offset:-1024
	global_load_dword v225, v[126:127], off offset:-512
	global_load_dword v226, v[126:127], off offset:0
	global_load_dword v227, v[126:127], off offset:512
	global_load_dword v228, v[126:127], off offset:1024
	global_load_dword v229, v[126:127], off offset:1536
	global_load_dword v230, v[126:127], off offset:2048
	global_load_dword v231, v[126:127], off offset:2560
	global_load_dword v232, v[126:127], off offset:3072
	global_load_dword v233, v[126:127], off offset:3584
	v_add_co_u32_e32 v126, vcc, 0x2000, v126
	s_nop 1
	v_addc_co_u32_e32 v127, vcc, 0, v127, vcc
	global_load_dword v234, v[126:127], off offset:-4096
	global_load_dword v235, v[126:127], off offset:-3584
	global_load_dword v236, v[126:127], off offset:-3072
	global_load_dword v237, v[126:127], off offset:-2560
	global_load_dword v238, v[126:127], off offset:-2048
	global_load_dword v239, v[126:127], off offset:-1536
	global_load_dword v240, v[126:127], off offset:-1024
	global_load_dword v241, v[126:127], off offset:-512
	global_load_dword v242, v[126:127], off offset:0
	global_load_dword v243, v[126:127], off offset:512
	global_load_dword v244, v[126:127], off offset:1024
	global_load_dword v245, v[126:127], off offset:1536
	global_load_dword v246, v[126:127], off offset:2048
	global_load_dword v247, v[126:127], off offset:2560
	global_load_dword v248, v[126:127], off offset:3072
	global_load_dword v249, v[126:127], off offset:3584
	v_add_co_u32_e32 v126, vcc, 0x2000, v126
	s_nop 1
	v_addc_co_u32_e32 v127, vcc, 0, v127, vcc
	ds_read2_b64 v[138:141], v81 offset0:0 offset1:68
	ds_read2_b64 v[142:145], v81 offset0:136 offset1:204
	ds_read2_b64 v[148:151], v81 offset0:1 offset1:69
	ds_read2_b64 v[152:155], v81 offset0:137 offset1:205
	ds_read2_b64 v[158:161], v81 offset0:2 offset1:70
	ds_read2_b64 v[162:165], v81 offset0:138 offset1:206
	ds_read2_b64 v[170:173], v81 offset0:3 offset1:71
	ds_read2_b64 v[174:177], v81 offset0:139 offset1:207
	s_waitcnt vmcnt(56)
	s_waitcnt lgkmcnt(6)
	v_fmac_f32_e32 v38, v182, v138
	v_fmac_f32_e32 v39, v182, v140
	v_fmac_f32_e32 v36, v182, v142
	v_fmac_f32_e32 v37, v182, v144
	v_fmac_f32_e32 v38, v183, v139
	v_fmac_f32_e32 v39, v183, v141
	v_fmac_f32_e32 v36, v183, v143
	v_fmac_f32_e32 v37, v183, v145
	ds_read2_b64 v[138:141], v81 offset0:4 offset1:72
	ds_read2_b64 v[142:145], v81 offset0:140 offset1:208
	s_waitcnt lgkmcnt(6)
; DI void attn_sample_task(LAS unsigned char* wl, int task, int l, ArgsP a, const bf16_t* Q, bf16_t* YB, int lane) {
;     ...
;     float o[4] = {0.f, 0.f, 0.f, 0.f};
;     for (int j = 0; j < 132; ++j) { const float v = (j < 128 ? cv + (size_t)j * 128 : nv + (size_t)(j - 128) * 128)[lane];
; #pragma unroll
;         for (int t = 0; t < 4; ++t) o[t] += ps[t * 136 + j] * v; }
	v_fmac_f32_e32 v38, v184, v148
	v_fmac_f32_e32 v39, v184, v150
	v_fmac_f32_e32 v36, v184, v152
	v_fmac_f32_e32 v37, v184, v154
	v_fmac_f32_e32 v38, v185, v149
	v_fmac_f32_e32 v39, v185, v151
	v_fmac_f32_e32 v36, v185, v153
	v_fmac_f32_e32 v37, v185, v155
	ds_read2_b64 v[148:151], v81 offset0:5 offset1:73
	ds_read2_b64 v[152:155], v81 offset0:141 offset1:209
	s_waitcnt lgkmcnt(6)
	v_fmac_f32_e32 v38, v186, v158
	v_fmac_f32_e32 v39, v186, v160
	v_fmac_f32_e32 v36, v186, v162
	v_fmac_f32_e32 v37, v186, v164
	v_fmac_f32_e32 v38, v187, v159
	v_fmac_f32_e32 v39, v187, v161
	v_fmac_f32_e32 v36, v187, v163
	v_fmac_f32_e32 v37, v187, v165
	ds_read2_b64 v[158:161], v81 offset0:6 offset1:74
	ds_read2_b64 v[162:165], v81 offset0:142 offset1:210
	s_waitcnt lgkmcnt(6)
	v_fmac_f32_e32 v38, v188, v170
	v_fmac_f32_e32 v39, v188, v172
	v_fmac_f32_e32 v36, v188, v174
	v_fmac_f32_e32 v37, v188, v176
	v_fmac_f32_e32 v38, v189, v171
	v_fmac_f32_e32 v39, v189, v173
	v_fmac_f32_e32 v36, v189, v175
	v_fmac_f32_e32 v37, v189, v177
	ds_read2_b64 v[170:173], v81 offset0:7 offset1:75
	ds_read2_b64 v[174:177], v81 offset0:143 offset1:211
	global_load_dword v182, v[126:127], off offset:-4096
	global_load_dword v183, v[126:127], off offset:-3584
	global_load_dword v184, v[126:127], off offset:-3072
	global_load_dword v185, v[126:127], off offset:-2560
	global_load_dword v186, v[126:127], off offset:-2048
	global_load_dword v187, v[126:127], off offset:-1536
	global_load_dword v188, v[126:127], off offset:-1024
	global_load_dword v189, v[126:127], off offset:-512
	s_waitcnt vmcnt(56)
	s_waitcnt lgkmcnt(6)
	v_fmac_f32_e32 v38, v190, v138
	v_fmac_f32_e32 v39, v190, v140
	v_fmac_f32_e32 v36, v190, v142
	v_fmac_f32_e32 v37, v190, v144
	v_fmac_f32_e32 v38, v191, v139
	v_fmac_f32_e32 v39, v191, v141
	v_fmac_f32_e32 v36, v191, v143
	v_fmac_f32_e32 v37, v191, v145
	ds_read2_b64 v[138:141], v81 offset0:8 offset1:76
	ds_read2_b64 v[142:145], v81 offset0:144 offset1:212
	s_waitcnt lgkmcnt(6)
	v_fmac_f32_e32 v38, v192, v148
	v_fmac_f32_e32 v39, v192, v150
	v_fmac_f32_e32 v36, v192, v152
	v_fmac_f32_e32 v37, v192, v154
	v_fmac_f32_e32 v38, v193, v149
	v_fmac_f32_e32 v39, v193, v151
	v_fmac_f32_e32 v36, v193, v153
	v_fmac_f32_e32 v37, v193, v155
	ds_read2_b64 v[148:151], v81 offset0:9 offset1:77
	ds_read2_b64 v[152:155], v81 offset0:145 offset1:213
	s_waitcnt lgkmcnt(6)
	v_fmac_f32_e32 v38, v198, v158
	v_fmac_f32_e32 v39, v198, v160
	v_fmac_f32_e32 v36, v198, v162
	v_fmac_f32_e32 v37, v198, v164
	v_fmac_f32_e32 v38, v199, v159
	v_fmac_f32_e32 v39, v199, v161
	v_fmac_f32_e32 v36, v199, v163
	v_fmac_f32_e32 v37, v199, v165
	ds_read2_b64 v[158:161], v81 offset0:10 offset1:78
	ds_read2_b64 v[162:165], v81 offset0:146 offset1:214
	s_waitcnt lgkmcnt(6)
	v_fmac_f32_e32 v38, v200, v170
	v_fmac_f32_e32 v39, v200, v172
	v_fmac_f32_e32 v36, v200, v174
	v_fmac_f32_e32 v37, v200, v176
	v_fmac_f32_e32 v38, v201, v171
	v_fmac_f32_e32 v39, v201, v173
	v_fmac_f32_e32 v36, v201, v175
	v_fmac_f32_e32 v37, v201, v177
	ds_read2_b64 v[170:173], v81 offset0:11 offset1:79
	ds_read2_b64 v[174:177], v81 offset0:147 offset1:215
	global_load_dword v190, v[126:127], off offset:0
	global_load_dword v191, v[126:127], off offset:512
	global_load_dword v192, v[126:127], off offset:1024
	global_load_dword v193, v[126:127], off offset:1536
	global_load_dword v198, v[126:127], off offset:2048
	global_load_dword v199, v[126:127], off offset:2560
	global_load_dword v200, v[126:127], off offset:3072
	global_load_dword v201, v[126:127], off offset:3584
	v_add_co_u32_e32 v126, vcc, 0x2000, v126
	s_nop 1
	v_addc_co_u32_e32 v127, vcc, 0, v127, vcc
	s_waitcnt vmcnt(56)
	s_waitcnt lgkmcnt(6)
	v_fmac_f32_e32 v38, v202, v138
	v_fmac_f32_e32 v39, v202, v140
	v_fmac_f32_e32 v36, v202, v142
	v_fmac_f32_e32 v37, v202, v144
	v_fmac_f32_e32 v38, v203, v139
	v_fmac_f32_e32 v39, v203, v141
	v_fmac_f32_e32 v36, v203, v143
	v_fmac_f32_e32 v37, v203, v145
	ds_read2_b64 v[138:141], v81 offset0:12 offset1:80
	ds_read2_b64 v[142:145], v81 offset0:148 offset1:216
	s_waitcnt lgkmcnt(6)
	v_fmac_f32_e32 v38, v204, v148
	v_fmac_f32_e32 v39, v204, v150
	v_fmac_f32_e32 v36, v204, v152
	v_fmac_f32_e32 v37, v204, v154
	v_fmac_f32_e32 v38, v205, v149
	v_fmac_f32_e32 v39, v205, v151
	v_fmac_f32_e32 v36, v205, v153
	v_fmac_f32_e32 v37, v205, v155
	ds_read2_b64 v[148:151], v81 offset0:13 offset1:81
	ds_read2_b64 v[152:155], v81 offset0:149 offset1:217
	s_waitcnt lgkmcnt(6)
	v_fmac_f32_e32 v38, v206, v158
	v_fmac_f32_e32 v39, v206, v160
	v_fmac_f32_e32 v36, v206, v162
	v_fmac_f32_e32 v37, v206, v164
	v_fmac_f32_e32 v38, v207, v159
	v_fmac_f32_e32 v39, v207, v161
	v_fmac_f32_e32 v36, v207, v163
	v_fmac_f32_e32 v37, v207, v165
	ds_read2_b64 v[158:161], v81 offset0:14 offset1:82
	ds_read2_b64 v[162:165], v81 offset0:150 offset1:218
	s_waitcnt lgkmcnt(6)
	v_fmac_f32_e32 v38, v208, v170
	v_fmac_f32_e32 v39, v208, v172
	v_fmac_f32_e32 v36, v208, v174
	v_fmac_f32_e32 v37, v208, v176
	v_fmac_f32_e32 v38, v209, v171
	v_fmac_f32_e32 v39, v209, v173
	v_fmac_f32_e32 v36, v209, v175
	v_fmac_f32_e32 v37, v209, v177
	ds_read2_b64 v[170:173], v81 offset0:15 offset1:83
	ds_read2_b64 v[174:177], v81 offset0:151 offset1:219
	global_load_dword v202, v[126:127], off offset:-4096
	global_load_dword v203, v[126:127], off offset:-3584
	global_load_dword v204, v[126:127], off offset:-3072
	global_load_dword v205, v[126:127], off offset:-2560
	global_load_dword v206, v[126:127], off offset:-2048
	global_load_dword v207, v[126:127], off offset:-1536
	global_load_dword v208, v[126:127], off offset:-1024
	global_load_dword v209, v[126:127], off offset:-512
	s_waitcnt vmcnt(56)
; DI void attn_sample_task(LAS unsigned char* wl, int task, int l, ArgsP a, const bf16_t* Q, bf16_t* YB, int lane) {
;     ...
;     float o[4] = {0.f, 0.f, 0.f, 0.f};
;     for (int j = 0; j < 132; ++j) { const float v = (j < 128 ? cv + (size_t)j * 128 : nv + (size_t)(j - 128) * 128)[lane];
; #pragma unroll
;         for (int t = 0; t < 4; ++t) o[t] += ps[t * 136 + j] * v; }
	s_waitcnt lgkmcnt(6)
	v_fmac_f32_e32 v38, v210, v138
	v_fmac_f32_e32 v39, v210, v140
	v_fmac_f32_e32 v36, v210, v142
	v_fmac_f32_e32 v37, v210, v144
	v_fmac_f32_e32 v38, v211, v139
	v_fmac_f32_e32 v39, v211, v141
	v_fmac_f32_e32 v36, v211, v143
	v_fmac_f32_e32 v37, v211, v145
	ds_read2_b64 v[138:141], v81 offset0:16 offset1:84
	ds_read2_b64 v[142:145], v81 offset0:152 offset1:220
	s_waitcnt lgkmcnt(6)
	v_fmac_f32_e32 v38, v212, v148
	v_fmac_f32_e32 v39, v212, v150
	v_fmac_f32_e32 v36, v212, v152
	v_fmac_f32_e32 v37, v212, v154
	v_fmac_f32_e32 v38, v213, v149
	v_fmac_f32_e32 v39, v213, v151
	v_fmac_f32_e32 v36, v213, v153
	v_fmac_f32_e32 v37, v213, v155
	ds_read2_b64 v[148:151], v81 offset0:17 offset1:85
	ds_read2_b64 v[152:155], v81 offset0:153 offset1:221
	s_waitcnt lgkmcnt(6)
	v_fmac_f32_e32 v38, v214, v158
	v_fmac_f32_e32 v39, v214, v160
	v_fmac_f32_e32 v36, v214, v162
	v_fmac_f32_e32 v37, v214, v164
	v_fmac_f32_e32 v38, v215, v159
	v_fmac_f32_e32 v39, v215, v161
	v_fmac_f32_e32 v36, v215, v163
	v_fmac_f32_e32 v37, v215, v165
	ds_read2_b64 v[158:161], v81 offset0:18 offset1:86
	ds_read2_b64 v[162:165], v81 offset0:154 offset1:222
	s_waitcnt lgkmcnt(6)
	v_fmac_f32_e32 v38, v216, v170
	v_fmac_f32_e32 v39, v216, v172
	v_fmac_f32_e32 v36, v216, v174
	v_fmac_f32_e32 v37, v216, v176
	v_fmac_f32_e32 v38, v217, v171
	v_fmac_f32_e32 v39, v217, v173
	v_fmac_f32_e32 v36, v217, v175
	v_fmac_f32_e32 v37, v217, v177
	ds_read2_b64 v[170:173], v81 offset0:19 offset1:87
	ds_read2_b64 v[174:177], v81 offset0:155 offset1:223
	global_load_dword v210, v[126:127], off offset:0
	global_load_dword v211, v[126:127], off offset:512
	global_load_dword v212, v[126:127], off offset:1024
	global_load_dword v213, v[126:127], off offset:1536
	global_load_dword v214, v[126:127], off offset:2048
	global_load_dword v215, v[126:127], off offset:2560
	global_load_dword v216, v[126:127], off offset:3072
	global_load_dword v217, v[126:127], off offset:3584
	v_add_co_u32_e32 v126, vcc, 0x2000, v126
	s_nop 1
	v_addc_co_u32_e32 v127, vcc, 0, v127, vcc
	s_waitcnt vmcnt(56)
	s_waitcnt lgkmcnt(6)
	v_fmac_f32_e32 v38, v218, v138
	v_fmac_f32_e32 v39, v218, v140
	v_fmac_f32_e32 v36, v218, v142
	v_fmac_f32_e32 v37, v218, v144
	v_fmac_f32_e32 v38, v219, v139
	v_fmac_f32_e32 v39, v219, v141
	v_fmac_f32_e32 v36, v219, v143
	v_fmac_f32_e32 v37, v219, v145
	ds_read2_b64 v[138:141], v81 offset0:20 offset1:88
	ds_read2_b64 v[142:145], v81 offset0:156 offset1:224
	s_waitcnt lgkmcnt(6)
	v_fmac_f32_e32 v38, v220, v148
	v_fmac_f32_e32 v39, v220, v150
	v_fmac_f32_e32 v36, v220, v152
	v_fmac_f32_e32 v37, v220, v154
	v_fmac_f32_e32 v38, v221, v149
	v_fmac_f32_e32 v39, v221, v151
	v_fmac_f32_e32 v36, v221, v153
	v_fmac_f32_e32 v37, v221, v155
	ds_read2_b64 v[148:151], v81 offset0:21 offset1:89
	ds_read2_b64 v[152:155], v81 offset0:157 offset1:225
	s_waitcnt lgkmcnt(6)
	v_fmac_f32_e32 v38, v222, v158
	v_fmac_f32_e32 v39, v222, v160
	v_fmac_f32_e32 v36, v222, v162
	v_fmac_f32_e32 v37, v222, v164
	v_fmac_f32_e32 v38, v223, v159
	v_fmac_f32_e32 v39, v223, v161
	v_fmac_f32_e32 v36, v223, v163
	v_fmac_f32_e32 v37, v223, v165
	ds_read2_b64 v[158:161], v81 offset0:22 offset1:90
	ds_read2_b64 v[162:165], v81 offset0:158 offset1:226
	s_waitcnt lgkmcnt(6)
	v_fmac_f32_e32 v38, v224, v170
	v_fmac_f32_e32 v39, v224, v172
	v_fmac_f32_e32 v36, v224, v174
	v_fmac_f32_e32 v37, v224, v176
	v_fmac_f32_e32 v38, v225, v171
	v_fmac_f32_e32 v39, v225, v173
	v_fmac_f32_e32 v36, v225, v175
	v_fmac_f32_e32 v37, v225, v177
	ds_read2_b64 v[170:173], v81 offset0:23 offset1:91
	ds_read2_b64 v[174:177], v81 offset0:159 offset1:227
	global_load_dword v218, v[126:127], off offset:-4096
	global_load_dword v219, v[126:127], off offset:-3584
	global_load_dword v220, v[126:127], off offset:-3072
	global_load_dword v221, v[126:127], off offset:-2560
	global_load_dword v222, v[126:127], off offset:-2048
	global_load_dword v223, v[126:127], off offset:-1536
	global_load_dword v224, v[126:127], off offset:-1024
	global_load_dword v225, v[126:127], off offset:-512
	s_waitcnt vmcnt(56)
	s_waitcnt lgkmcnt(6)
	v_fmac_f32_e32 v38, v226, v138
	v_fmac_f32_e32 v39, v226, v140
	v_fmac_f32_e32 v36, v226, v142
	v_fmac_f32_e32 v37, v226, v144
	v_fmac_f32_e32 v38, v227, v139
	v_fmac_f32_e32 v39, v227, v141
	v_fmac_f32_e32 v36, v227, v143
	v_fmac_f32_e32 v37, v227, v145
	ds_read2_b64 v[138:141], v81 offset0:24 offset1:92
	ds_read2_b64 v[142:145], v81 offset0:160 offset1:228
	s_waitcnt lgkmcnt(6)
	v_fmac_f32_e32 v38, v228, v148
	v_fmac_f32_e32 v39, v228, v150
	v_fmac_f32_e32 v36, v228, v152
	v_fmac_f32_e32 v37, v228, v154
	v_fmac_f32_e32 v38, v229, v149
	v_fmac_f32_e32 v39, v229, v151
	v_fmac_f32_e32 v36, v229, v153
	v_fmac_f32_e32 v37, v229, v155
	ds_read2_b64 v[148:151], v81 offset0:25 offset1:93
	ds_read2_b64 v[152:155], v81 offset0:161 offset1:229
	s_waitcnt lgkmcnt(6)
	v_fmac_f32_e32 v38, v230, v158
	v_fmac_f32_e32 v39, v230, v160
	v_fmac_f32_e32 v36, v230, v162
	v_fmac_f32_e32 v37, v230, v164
	v_fmac_f32_e32 v38, v231, v159
	v_fmac_f32_e32 v39, v231, v161
	v_fmac_f32_e32 v36, v231, v163
	v_fmac_f32_e32 v37, v231, v165
	ds_read2_b64 v[158:161], v81 offset0:26 offset1:94
	ds_read2_b64 v[162:165], v81 offset0:162 offset1:230
	s_waitcnt lgkmcnt(6)
; DI void attn_sample_task(LAS unsigned char* wl, int task, int l, ArgsP a, const bf16_t* Q, bf16_t* YB, int lane) {
;     ...
;     float o[4] = {0.f, 0.f, 0.f, 0.f};
;     for (int j = 0; j < 132; ++j) { const float v = (j < 128 ? cv + (size_t)j * 128 : nv + (size_t)(j - 128) * 128)[lane];
; #pragma unroll
;         for (int t = 0; t < 4; ++t) o[t] += ps[t * 136 + j] * v; }
	v_fmac_f32_e32 v38, v232, v170
	v_fmac_f32_e32 v39, v232, v172
	v_fmac_f32_e32 v36, v232, v174
	v_fmac_f32_e32 v37, v232, v176
	v_fmac_f32_e32 v38, v233, v171
	v_fmac_f32_e32 v39, v233, v173
	v_fmac_f32_e32 v36, v233, v175
	v_fmac_f32_e32 v37, v233, v177
	ds_read2_b64 v[170:173], v81 offset0:27 offset1:95
	ds_read2_b64 v[174:177], v81 offset0:163 offset1:231
	global_load_dword v226, v[126:127], off offset:0
	global_load_dword v227, v[126:127], off offset:512
	global_load_dword v228, v[126:127], off offset:1024
	global_load_dword v229, v[126:127], off offset:1536
	global_load_dword v230, v[126:127], off offset:2048
	global_load_dword v231, v[126:127], off offset:2560
	global_load_dword v232, v[126:127], off offset:3072
	global_load_dword v233, v[126:127], off offset:3584
	v_add_co_u32_e32 v126, vcc, 0x2000, v126
	s_nop 1
	v_addc_co_u32_e32 v127, vcc, 0, v127, vcc
	s_waitcnt vmcnt(56)
	s_waitcnt lgkmcnt(6)
	v_fmac_f32_e32 v38, v234, v138
	v_fmac_f32_e32 v39, v234, v140
	v_fmac_f32_e32 v36, v234, v142
	v_fmac_f32_e32 v37, v234, v144
	v_fmac_f32_e32 v38, v235, v139
	v_fmac_f32_e32 v39, v235, v141
	v_fmac_f32_e32 v36, v235, v143
	v_fmac_f32_e32 v37, v235, v145
	ds_read2_b64 v[138:141], v81 offset0:28 offset1:96
	ds_read2_b64 v[142:145], v81 offset0:164 offset1:232
	s_waitcnt lgkmcnt(6)
	v_fmac_f32_e32 v38, v236, v148
	v_fmac_f32_e32 v39, v236, v150
	v_fmac_f32_e32 v36, v236, v152
	v_fmac_f32_e32 v37, v236, v154
	v_fmac_f32_e32 v38, v237, v149
	v_fmac_f32_e32 v39, v237, v151
	v_fmac_f32_e32 v36, v237, v153
	v_fmac_f32_e32 v37, v237, v155
	ds_read2_b64 v[148:151], v81 offset0:29 offset1:97
	ds_read2_b64 v[152:155], v81 offset0:165 offset1:233
	s_waitcnt lgkmcnt(6)
	v_fmac_f32_e32 v38, v238, v158
	v_fmac_f32_e32 v39, v238, v160
	v_fmac_f32_e32 v36, v238, v162
	v_fmac_f32_e32 v37, v238, v164
	v_fmac_f32_e32 v38, v239, v159
	v_fmac_f32_e32 v39, v239, v161
	v_fmac_f32_e32 v36, v239, v163
	v_fmac_f32_e32 v37, v239, v165
	ds_read2_b64 v[158:161], v81 offset0:30 offset1:98
	ds_read2_b64 v[162:165], v81 offset0:166 offset1:234
	s_waitcnt lgkmcnt(6)
	v_fmac_f32_e32 v38, v240, v170
	v_fmac_f32_e32 v39, v240, v172
	v_fmac_f32_e32 v36, v240, v174
	v_fmac_f32_e32 v37, v240, v176
	v_fmac_f32_e32 v38, v241, v171
	v_fmac_f32_e32 v39, v241, v173
	v_fmac_f32_e32 v36, v241, v175
	v_fmac_f32_e32 v37, v241, v177
	ds_read2_b64 v[170:173], v81 offset0:31 offset1:99
	ds_read2_b64 v[174:177], v81 offset0:167 offset1:235
	global_load_dword v234, v[126:127], off offset:-4096
	global_load_dword v235, v[126:127], off offset:-3584
	global_load_dword v236, v[126:127], off offset:-3072
	global_load_dword v237, v[126:127], off offset:-2560
	global_load_dword v238, v[126:127], off offset:-2048
	global_load_dword v239, v[126:127], off offset:-1536
	global_load_dword v240, v[126:127], off offset:-1024
	global_load_dword v241, v[126:127], off offset:-512
	s_waitcnt vmcnt(56)
	s_waitcnt lgkmcnt(6)
	v_fmac_f32_e32 v38, v242, v138
	v_fmac_f32_e32 v39, v242, v140
	v_fmac_f32_e32 v36, v242, v142
	v_fmac_f32_e32 v37, v242, v144
	v_fmac_f32_e32 v38, v243, v139
	v_fmac_f32_e32 v39, v243, v141
	v_fmac_f32_e32 v36, v243, v143
	v_fmac_f32_e32 v37, v243, v145
	ds_read2_b64 v[138:141], v82 offset0:0 offset1:68
	ds_read2_b64 v[142:145], v82 offset0:136 offset1:204
	s_waitcnt lgkmcnt(6)
	v_fmac_f32_e32 v38, v244, v148
	v_fmac_f32_e32 v39, v244, v150
	v_fmac_f32_e32 v36, v244, v152
	v_fmac_f32_e32 v37, v244, v154
	v_fmac_f32_e32 v38, v245, v149
	v_fmac_f32_e32 v39, v245, v151
	v_fmac_f32_e32 v36, v245, v153
	v_fmac_f32_e32 v37, v245, v155
	ds_read2_b64 v[148:151], v82 offset0:1 offset1:69
	ds_read2_b64 v[152:155], v82 offset0:137 offset1:205
	s_waitcnt lgkmcnt(6)
	v_fmac_f32_e32 v38, v246, v158
	v_fmac_f32_e32 v39, v246, v160
	v_fmac_f32_e32 v36, v246, v162
	v_fmac_f32_e32 v37, v246, v164
	v_fmac_f32_e32 v38, v247, v159
	v_fmac_f32_e32 v39, v247, v161
	v_fmac_f32_e32 v36, v247, v163
	v_fmac_f32_e32 v37, v247, v165
	ds_read2_b64 v[158:161], v82 offset0:2 offset1:70
	ds_read2_b64 v[162:165], v82 offset0:138 offset1:206
	s_waitcnt lgkmcnt(6)
	v_fmac_f32_e32 v38, v248, v170
	v_fmac_f32_e32 v39, v248, v172
	v_fmac_f32_e32 v36, v248, v174
	v_fmac_f32_e32 v37, v248, v176
	v_fmac_f32_e32 v38, v249, v171
	v_fmac_f32_e32 v39, v249, v173
	v_fmac_f32_e32 v36, v249, v175
	v_fmac_f32_e32 v37, v249, v177
	ds_read2_b64 v[170:173], v82 offset0:3 offset1:71
	ds_read2_b64 v[174:177], v82 offset0:139 offset1:207
	global_load_dword v242, v[126:127], off offset:0
	global_load_dword v243, v[126:127], off offset:512
	global_load_dword v244, v[126:127], off offset:1024
	global_load_dword v245, v[126:127], off offset:1536
	global_load_dword v246, v[126:127], off offset:2048
	global_load_dword v247, v[126:127], off offset:2560
	global_load_dword v248, v[126:127], off offset:3072
	global_load_dword v249, v[126:127], off offset:3584
	global_load_dword v250, v[124:125], off
	global_load_dword v251, v[124:125], off offset:512
	global_load_dword v252, v[124:125], off offset:1024
	global_load_dword v253, v[124:125], off offset:1536
	s_waitcnt vmcnt(60)
	s_waitcnt lgkmcnt(6)
	v_fmac_f32_e32 v38, v182, v138
	v_fmac_f32_e32 v39, v182, v140
	v_fmac_f32_e32 v36, v182, v142
	v_fmac_f32_e32 v37, v182, v144
	v_fmac_f32_e32 v38, v183, v139
	v_fmac_f32_e32 v39, v183, v141
	v_fmac_f32_e32 v36, v183, v143
	v_fmac_f32_e32 v37, v183, v145
	ds_read2_b64 v[138:141], v82 offset0:4 offset1:72
	ds_read2_b64 v[142:145], v82 offset0:140 offset1:208
	s_waitcnt lgkmcnt(6)
; DI void attn_sample_task(LAS unsigned char* wl, int task, int l, ArgsP a, const bf16_t* Q, bf16_t* YB, int lane) {
;     ...
;     float o[4] = {0.f, 0.f, 0.f, 0.f};
;     for (int j = 0; j < 132; ++j) { const float v = (j < 128 ? cv + (size_t)j * 128 : nv + (size_t)(j - 128) * 128)[lane];
; #pragma unroll
;         for (int t = 0; t < 4; ++t) o[t] += ps[t * 136 + j] * v; }
	v_fmac_f32_e32 v38, v184, v148
	v_fmac_f32_e32 v39, v184, v150
	v_fmac_f32_e32 v36, v184, v152
	v_fmac_f32_e32 v37, v184, v154
	v_fmac_f32_e32 v38, v185, v149
	v_fmac_f32_e32 v39, v185, v151
	v_fmac_f32_e32 v36, v185, v153
	v_fmac_f32_e32 v37, v185, v155
	ds_read2_b64 v[148:151], v82 offset0:5 offset1:73
	ds_read2_b64 v[152:155], v82 offset0:141 offset1:209
	s_waitcnt lgkmcnt(6)
	v_fmac_f32_e32 v38, v186, v158
	v_fmac_f32_e32 v39, v186, v160
	v_fmac_f32_e32 v36, v186, v162
	v_fmac_f32_e32 v37, v186, v164
	v_fmac_f32_e32 v38, v187, v159
	v_fmac_f32_e32 v39, v187, v161
	v_fmac_f32_e32 v36, v187, v163
	v_fmac_f32_e32 v37, v187, v165
	ds_read2_b64 v[158:161], v82 offset0:6 offset1:74
	ds_read2_b64 v[162:165], v82 offset0:142 offset1:210
	s_waitcnt lgkmcnt(6)
	v_fmac_f32_e32 v38, v188, v170
	v_fmac_f32_e32 v39, v188, v172
	v_fmac_f32_e32 v36, v188, v174
	v_fmac_f32_e32 v37, v188, v176
	v_fmac_f32_e32 v38, v189, v171
	v_fmac_f32_e32 v39, v189, v173
	v_fmac_f32_e32 v36, v189, v175
	v_fmac_f32_e32 v37, v189, v177
	ds_read2_b64 v[170:173], v82 offset0:7 offset1:75
	ds_read2_b64 v[174:177], v82 offset0:143 offset1:211
	s_waitcnt vmcnt(52)
	s_waitcnt lgkmcnt(6)
	v_fmac_f32_e32 v38, v190, v138
	v_fmac_f32_e32 v39, v190, v140
	v_fmac_f32_e32 v36, v190, v142
	v_fmac_f32_e32 v37, v190, v144
	v_fmac_f32_e32 v38, v191, v139
	v_fmac_f32_e32 v39, v191, v141
	v_fmac_f32_e32 v36, v191, v143
	v_fmac_f32_e32 v37, v191, v145
	ds_read2_b64 v[138:141], v82 offset0:8 offset1:76
	ds_read2_b64 v[142:145], v82 offset0:144 offset1:212
	s_waitcnt lgkmcnt(6)
	v_fmac_f32_e32 v38, v192, v148
	v_fmac_f32_e32 v39, v192, v150
	v_fmac_f32_e32 v36, v192, v152
	v_fmac_f32_e32 v37, v192, v154
	v_fmac_f32_e32 v38, v193, v149
	v_fmac_f32_e32 v39, v193, v151
	v_fmac_f32_e32 v36, v193, v153
	v_fmac_f32_e32 v37, v193, v155
	ds_read2_b64 v[148:151], v82 offset0:9 offset1:77
	ds_read2_b64 v[152:155], v82 offset0:145 offset1:213
	s_waitcnt lgkmcnt(6)
	v_fmac_f32_e32 v38, v198, v158
	v_fmac_f32_e32 v39, v198, v160
	v_fmac_f32_e32 v36, v198, v162
	v_fmac_f32_e32 v37, v198, v164
	v_fmac_f32_e32 v38, v199, v159
	v_fmac_f32_e32 v39, v199, v161
	v_fmac_f32_e32 v36, v199, v163
	v_fmac_f32_e32 v37, v199, v165
	ds_read2_b64 v[158:161], v82 offset0:10 offset1:78
	ds_read2_b64 v[162:165], v82 offset0:146 offset1:214
	s_waitcnt lgkmcnt(6)
	v_fmac_f32_e32 v38, v200, v170
	v_fmac_f32_e32 v39, v200, v172
	v_fmac_f32_e32 v36, v200, v174
	v_fmac_f32_e32 v37, v200, v176
	v_fmac_f32_e32 v38, v201, v171
	v_fmac_f32_e32 v39, v201, v173
	v_fmac_f32_e32 v36, v201, v175
	v_fmac_f32_e32 v37, v201, v177
	ds_read2_b64 v[170:173], v82 offset0:11 offset1:79
	ds_read2_b64 v[174:177], v82 offset0:147 offset1:215
	s_waitcnt vmcnt(44)
	s_waitcnt lgkmcnt(6)
	v_fmac_f32_e32 v38, v202, v138
	v_fmac_f32_e32 v39, v202, v140
	v_fmac_f32_e32 v36, v202, v142
	v_fmac_f32_e32 v37, v202, v144
	v_fmac_f32_e32 v38, v203, v139
	v_fmac_f32_e32 v39, v203, v141
	v_fmac_f32_e32 v36, v203, v143
	v_fmac_f32_e32 v37, v203, v145
	ds_read2_b64 v[138:141], v82 offset0:12 offset1:80
	ds_read2_b64 v[142:145], v82 offset0:148 offset1:216
	s_waitcnt lgkmcnt(6)
	v_fmac_f32_e32 v38, v204, v148
	v_fmac_f32_e32 v39, v204, v150
	v_fmac_f32_e32 v36, v204, v152
	v_fmac_f32_e32 v37, v204, v154
	v_fmac_f32_e32 v38, v205, v149
	v_fmac_f32_e32 v39, v205, v151
	v_fmac_f32_e32 v36, v205, v153
	v_fmac_f32_e32 v37, v205, v155
	ds_read2_b64 v[148:151], v82 offset0:13 offset1:81
	ds_read2_b64 v[152:155], v82 offset0:149 offset1:217
	s_waitcnt lgkmcnt(6)
	v_fmac_f32_e32 v38, v206, v158
	v_fmac_f32_e32 v39, v206, v160
	v_fmac_f32_e32 v36, v206, v162
	v_fmac_f32_e32 v37, v206, v164
	v_fmac_f32_e32 v38, v207, v159
	v_fmac_f32_e32 v39, v207, v161
	v_fmac_f32_e32 v36, v207, v163
	v_fmac_f32_e32 v37, v207, v165
	ds_read2_b64 v[158:161], v82 offset0:14 offset1:82
	ds_read2_b64 v[162:165], v82 offset0:150 offset1:218
	s_waitcnt lgkmcnt(6)
	v_fmac_f32_e32 v38, v208, v170
	v_fmac_f32_e32 v39, v208, v172
	v_fmac_f32_e32 v36, v208, v174
	v_fmac_f32_e32 v37, v208, v176
	v_fmac_f32_e32 v38, v209, v171
	v_fmac_f32_e32 v39, v209, v173
	v_fmac_f32_e32 v36, v209, v175
	v_fmac_f32_e32 v37, v209, v177
	ds_read2_b64 v[170:173], v82 offset0:15 offset1:83
	ds_read2_b64 v[174:177], v82 offset0:151 offset1:219
	s_waitcnt vmcnt(36)
	s_waitcnt lgkmcnt(6)
	v_fmac_f32_e32 v38, v210, v138
	v_fmac_f32_e32 v39, v210, v140
	v_fmac_f32_e32 v36, v210, v142
	v_fmac_f32_e32 v37, v210, v144
	v_fmac_f32_e32 v38, v211, v139
	v_fmac_f32_e32 v39, v211, v141
	v_fmac_f32_e32 v36, v211, v143
	v_fmac_f32_e32 v37, v211, v145
	ds_read2_b64 v[138:141], v82 offset0:16 offset1:84
	ds_read2_b64 v[142:145], v82 offset0:152 offset1:220
	s_waitcnt lgkmcnt(6)
	v_fmac_f32_e32 v38, v212, v148
	v_fmac_f32_e32 v39, v212, v150
	v_fmac_f32_e32 v36, v212, v152
	v_fmac_f32_e32 v37, v212, v154
	v_fmac_f32_e32 v38, v213, v149
	v_fmac_f32_e32 v39, v213, v151
	v_fmac_f32_e32 v36, v213, v153
	v_fmac_f32_e32 v37, v213, v155
	ds_read2_b64 v[148:151], v82 offset0:17 offset1:85
	ds_read2_b64 v[152:155], v82 offset0:153 offset1:221
	s_waitcnt lgkmcnt(6)
	v_fmac_f32_e32 v38, v214, v158
	v_fmac_f32_e32 v39, v214, v160
	v_fmac_f32_e32 v36, v214, v162
	v_fmac_f32_e32 v37, v214, v164
	v_fmac_f32_e32 v38, v215, v159
	v_fmac_f32_e32 v39, v215, v161
	v_fmac_f32_e32 v36, v215, v163
	v_fmac_f32_e32 v37, v215, v165
	ds_read2_b64 v[158:161], v82 offset0:18 offset1:86
	ds_read2_b64 v[162:165], v82 offset0:154 offset1:222
	s_waitcnt lgkmcnt(6)
	v_fmac_f32_e32 v38, v216, v170
	v_fmac_f32_e32 v39, v216, v172
	v_fmac_f32_e32 v36, v216, v174
	v_fmac_f32_e32 v37, v216, v176
	v_fmac_f32_e32 v38, v217, v171
	v_fmac_f32_e32 v39, v217, v173
	v_fmac_f32_e32 v36, v217, v175
	v_fmac_f32_e32 v37, v217, v177
	ds_read2_b64 v[170:173], v82 offset0:19 offset1:87
	ds_read2_b64 v[174:177], v82 offset0:155 offset1:223
	s_waitcnt vmcnt(28)
; DI void attn_sample_task(LAS unsigned char* wl, int task, int l, ArgsP a, const bf16_t* Q, bf16_t* YB, int lane) {
;     ...
;     float o[4] = {0.f, 0.f, 0.f, 0.f};
;     for (int j = 0; j < 132; ++j) { const float v = (j < 128 ? cv + (size_t)j * 128 : nv + (size_t)(j - 128) * 128)[lane];
; #pragma unroll
;         for (int t = 0; t < 4; ++t) o[t] += ps[t * 136 + j] * v; }
	s_waitcnt lgkmcnt(6)
	v_fmac_f32_e32 v38, v218, v138
	v_fmac_f32_e32 v39, v218, v140
	v_fmac_f32_e32 v36, v218, v142
	v_fmac_f32_e32 v37, v218, v144
	v_fmac_f32_e32 v38, v219, v139
	v_fmac_f32_e32 v39, v219, v141
	v_fmac_f32_e32 v36, v219, v143
	v_fmac_f32_e32 v37, v219, v145
	ds_read2_b64 v[138:141], v82 offset0:20 offset1:88
	ds_read2_b64 v[142:145], v82 offset0:156 offset1:224
	s_waitcnt lgkmcnt(6)
	v_fmac_f32_e32 v38, v220, v148
	v_fmac_f32_e32 v39, v220, v150
	v_fmac_f32_e32 v36, v220, v152
	v_fmac_f32_e32 v37, v220, v154
	v_fmac_f32_e32 v38, v221, v149
	v_fmac_f32_e32 v39, v221, v151
	v_fmac_f32_e32 v36, v221, v153
	v_fmac_f32_e32 v37, v221, v155
	ds_read2_b64 v[148:151], v82 offset0:21 offset1:89
	ds_read2_b64 v[152:155], v82 offset0:157 offset1:225
	s_waitcnt lgkmcnt(6)
	v_fmac_f32_e32 v38, v222, v158
	v_fmac_f32_e32 v39, v222, v160
	v_fmac_f32_e32 v36, v222, v162
	v_fmac_f32_e32 v37, v222, v164
	v_fmac_f32_e32 v38, v223, v159
	v_fmac_f32_e32 v39, v223, v161
	v_fmac_f32_e32 v36, v223, v163
	v_fmac_f32_e32 v37, v223, v165
	ds_read2_b64 v[158:161], v82 offset0:22 offset1:90
	ds_read2_b64 v[162:165], v82 offset0:158 offset1:226
	s_waitcnt lgkmcnt(6)
	v_fmac_f32_e32 v38, v224, v170
	v_fmac_f32_e32 v39, v224, v172
	v_fmac_f32_e32 v36, v224, v174
	v_fmac_f32_e32 v37, v224, v176
	v_fmac_f32_e32 v38, v225, v171
	v_fmac_f32_e32 v39, v225, v173
	v_fmac_f32_e32 v36, v225, v175
	v_fmac_f32_e32 v37, v225, v177
	ds_read2_b64 v[170:173], v82 offset0:23 offset1:91
	ds_read2_b64 v[174:177], v82 offset0:159 offset1:227
	s_waitcnt vmcnt(20)
	s_waitcnt lgkmcnt(6)
	v_fmac_f32_e32 v38, v226, v138
	v_fmac_f32_e32 v39, v226, v140
	v_fmac_f32_e32 v36, v226, v142
	v_fmac_f32_e32 v37, v226, v144
	v_fmac_f32_e32 v38, v227, v139
	v_fmac_f32_e32 v39, v227, v141
	v_fmac_f32_e32 v36, v227, v143
	v_fmac_f32_e32 v37, v227, v145
	ds_read2_b64 v[138:141], v82 offset0:24 offset1:92
	ds_read2_b64 v[142:145], v82 offset0:160 offset1:228
	s_waitcnt lgkmcnt(6)
	v_fmac_f32_e32 v38, v228, v148
	v_fmac_f32_e32 v39, v228, v150
	v_fmac_f32_e32 v36, v228, v152
	v_fmac_f32_e32 v37, v228, v154
	v_fmac_f32_e32 v38, v229, v149
	v_fmac_f32_e32 v39, v229, v151
	v_fmac_f32_e32 v36, v229, v153
	v_fmac_f32_e32 v37, v229, v155
	ds_read2_b64 v[148:151], v82 offset0:25 offset1:93
	ds_read2_b64 v[152:155], v82 offset0:161 offset1:229
	s_waitcnt lgkmcnt(6)
	v_fmac_f32_e32 v38, v230, v158
	v_fmac_f32_e32 v39, v230, v160
	v_fmac_f32_e32 v36, v230, v162
	v_fmac_f32_e32 v37, v230, v164
	v_fmac_f32_e32 v38, v231, v159
	v_fmac_f32_e32 v39, v231, v161
	v_fmac_f32_e32 v36, v231, v163
	v_fmac_f32_e32 v37, v231, v165
	ds_read2_b64 v[158:161], v82 offset0:26 offset1:94
	ds_read2_b64 v[162:165], v82 offset0:162 offset1:230
	s_waitcnt lgkmcnt(6)
	v_fmac_f32_e32 v38, v232, v170
	v_fmac_f32_e32 v39, v232, v172
	v_fmac_f32_e32 v36, v232, v174
	v_fmac_f32_e32 v37, v232, v176
	v_fmac_f32_e32 v38, v233, v171
	v_fmac_f32_e32 v39, v233, v173
	v_fmac_f32_e32 v36, v233, v175
	v_fmac_f32_e32 v37, v233, v177
	ds_read2_b64 v[170:173], v82 offset0:27 offset1:95
	ds_read2_b64 v[174:177], v82 offset0:163 offset1:231
	s_waitcnt vmcnt(12)
	s_waitcnt lgkmcnt(6)
	v_fmac_f32_e32 v38, v234, v138
	v_fmac_f32_e32 v39, v234, v140
	v_fmac_f32_e32 v36, v234, v142
	v_fmac_f32_e32 v37, v234, v144
	v_fmac_f32_e32 v38, v235, v139
	v_fmac_f32_e32 v39, v235, v141
	v_fmac_f32_e32 v36, v235, v143
	v_fmac_f32_e32 v37, v235, v145
	ds_read2_b64 v[138:141], v82 offset0:28 offset1:96
	ds_read2_b64 v[142:145], v82 offset0:164 offset1:232
	s_waitcnt lgkmcnt(6)
	v_fmac_f32_e32 v38, v236, v148
	v_fmac_f32_e32 v39, v236, v150
	v_fmac_f32_e32 v36, v236, v152
	v_fmac_f32_e32 v37, v236, v154
	v_fmac_f32_e32 v38, v237, v149
	v_fmac_f32_e32 v39, v237, v151
	v_fmac_f32_e32 v36, v237, v153
	v_fmac_f32_e32 v37, v237, v155
	ds_read2_b64 v[148:151], v82 offset0:29 offset1:97
	ds_read2_b64 v[152:155], v82 offset0:165 offset1:233
	s_waitcnt lgkmcnt(6)
	v_fmac_f32_e32 v38, v238, v158
	v_fmac_f32_e32 v39, v238, v160
	v_fmac_f32_e32 v36, v238, v162
	v_fmac_f32_e32 v37, v238, v164
	v_fmac_f32_e32 v38, v239, v159
	v_fmac_f32_e32 v39, v239, v161
	v_fmac_f32_e32 v36, v239, v163
	v_fmac_f32_e32 v37, v239, v165
	ds_read2_b64 v[158:161], v82 offset0:30 offset1:98
	ds_read2_b64 v[162:165], v82 offset0:166 offset1:234
	s_waitcnt lgkmcnt(6)
	v_fmac_f32_e32 v38, v240, v170
	v_fmac_f32_e32 v39, v240, v172
	v_fmac_f32_e32 v36, v240, v174
	v_fmac_f32_e32 v37, v240, v176
	v_fmac_f32_e32 v38, v241, v171
	v_fmac_f32_e32 v39, v241, v173
	v_fmac_f32_e32 v36, v241, v175
	v_fmac_f32_e32 v37, v241, v177
	ds_read2_b64 v[170:173], v82 offset0:31 offset1:99
	ds_read2_b64 v[174:177], v82 offset0:167 offset1:235
	s_waitcnt vmcnt(4)
	s_waitcnt lgkmcnt(6)
	v_fmac_f32_e32 v38, v242, v138
	v_fmac_f32_e32 v39, v242, v140
	v_fmac_f32_e32 v36, v242, v142
	v_fmac_f32_e32 v37, v242, v144
	v_fmac_f32_e32 v38, v243, v139
	v_fmac_f32_e32 v39, v243, v141
	v_fmac_f32_e32 v36, v243, v143
	v_fmac_f32_e32 v37, v243, v145
	ds_read2_b64 v[138:141], v82 offset0:32 offset1:100
	ds_read2_b64 v[142:145], v82 offset0:168 offset1:236
	s_waitcnt lgkmcnt(6)
	v_fmac_f32_e32 v38, v244, v148
	v_fmac_f32_e32 v39, v244, v150
	v_fmac_f32_e32 v36, v244, v152
	v_fmac_f32_e32 v37, v244, v154
	v_fmac_f32_e32 v38, v245, v149
	v_fmac_f32_e32 v39, v245, v151
	v_fmac_f32_e32 v36, v245, v153
	v_fmac_f32_e32 v37, v245, v155
	ds_read2_b64 v[148:151], v82 offset0:33 offset1:101
	ds_read2_b64 v[152:155], v82 offset0:169 offset1:237
	s_waitcnt lgkmcnt(6)
	v_fmac_f32_e32 v38, v246, v158
	v_fmac_f32_e32 v39, v246, v160
	v_fmac_f32_e32 v36, v246, v162
	v_fmac_f32_e32 v37, v246, v164
	v_fmac_f32_e32 v38, v247, v159
	v_fmac_f32_e32 v39, v247, v161
	v_fmac_f32_e32 v36, v247, v163
	v_fmac_f32_e32 v37, v247, v165
	s_waitcnt lgkmcnt(4)
	v_fmac_f32_e32 v38, v248, v170
	v_fmac_f32_e32 v39, v248, v172
	v_fmac_f32_e32 v36, v248, v174
	v_fmac_f32_e32 v37, v248, v176
	v_fmac_f32_e32 v38, v249, v171
	v_fmac_f32_e32 v39, v249, v173
	v_fmac_f32_e32 v36, v249, v175
	v_fmac_f32_e32 v37, v249, v177
	s_waitcnt vmcnt(0)
	s_waitcnt lgkmcnt(2)
	v_fmac_f32_e32 v38, v250, v138
	v_fmac_f32_e32 v39, v250, v140
	v_fmac_f32_e32 v36, v250, v142
	v_fmac_f32_e32 v37, v250, v144
	v_fmac_f32_e32 v38, v251, v139
	v_fmac_f32_e32 v39, v251, v141
	v_fmac_f32_e32 v36, v251, v143
	v_fmac_f32_e32 v37, v251, v145
	s_waitcnt lgkmcnt(0)
	v_fmac_f32_e32 v38, v252, v148
	v_fmac_f32_e32 v39, v252, v150
	v_fmac_f32_e32 v36, v252, v152
	v_fmac_f32_e32 v37, v252, v154
	v_fmac_f32_e32 v38, v253, v149
	v_fmac_f32_e32 v39, v253, v151
	v_fmac_f32_e32 v36, v253, v153
	v_fmac_f32_e32 v37, v253, v155
	s_branch .LBB0_967
